# MLA static s_setprio 1 for waves 0-3 (older half) instead of waves 4-7, everything else as v37
# speedup vs baseline: 1.0038x; 1.0026x over previous
; __device__ __forceinline__ int opaque_tid() { int t = threadIdx.x; asm volatile("" : "+v"(t)); return t; }
; __device__ __forceinline__ void mla_unit(char* lds, const bf16_t* __restrict__ Qp, const bf16_t* __restrict__ Knp, const bf16_t* __restrict__ Vp, ...
;     ...
;   const int tid = opaque_tid(), wid = __builtin_amdgcn_readfirstlane(tid >> 6), lane = tid & 63, r32 = lane & 31, hi = lane >> 5;
; __global__ void __launch_bounds__(NWAVES * 64, 2) fwd_mega(Args args) {
;     ...
;             for (int rep = 0; rep < REP_MLA; ++rep) for (int u = vcu; u < 1024; u += G) {
;                 const int bh = u >> 5, qb = u & 31, b = bh >> 4, h = bh & 15;
;                 const size_t tok0 = (size_t)b * SEQ + qb * 256, key0 = (size_t)b * SEQ;
.LBB0_236:
	v_mov_b32_e32 v50, v252
	s_ashr_i32 s6, s74, 9
	v_readfirstlane_b32 s0, v50
	s_ashr_i32 s8, s0, 6
	s_cmp_gt_u32 s8, 3
	s_cbranch_scc1 .Lmla_prio_skip
	s_setprio 1
